# FFN up/down mainloops rewritten: 16x16x32 bf16 MFMA on XOR-swizzled 128B-row LDS image, ds_write/global_load interleaved under MFMAs
# speedup vs baseline: 1.0238x; 1.0238x over previous
; DI int otid() { int t = threadIdx.x; asm volatile("" : "+v"(t)); return t; }
; template <bool SWAP, bool HALF>
; DI void gemm_mainloop(const GemmDesc& d, int m0, int n0, bf16_t* smem, f32x16 (&acc)[2][2], int dry) {
;   const int t = otid(), lane = t & 63, w = t >> 6, wm = w >> 1, wn = w & 1, r = lane & 31, hh = lane >> 5;
;   const int lrow = t >> 3, lkc = t & 7;
;   const bf16_t* ap[4]; const bf16_t* bp[4];
; #pragma unroll
;   for (int i = 0; i < 4; ++i) {
;     int am = m0 + lrow + 32 * i; am = am < M ? am : M - 1;
;     ap[i] = d.A + (size_t)am * d.lda + lkc * 8 + (d.a_grp ? (n0 / d.a_grp) * d.a_grp : 0);
;     bp[i] = d.Bt + (size_t)(n0 + lrow + 32 * i) * d.ldb + lkc * 8;
;   }
; #pragma unroll
;   for (int a = 0; a < 2; ++a)
; #pragma unroll
;     for (int b = 0; b < 2; ++b)
; #pragma unroll
;       for (int i = 0; i < 16; ++i) acc[a][b][i] = 0.f;
;   u32x4 ra0[4], rb0[4], ra1[4], rb1[4];
;   const int nk = d.K >> 6;
;   const int lds_w = lrow * LST + lkc * 8;
;     ...
;   gl(ra0, rb0, 0);
;   gl(ra1, rb1, 1);
;   lw(ra0, rb0, 0);
;   gl(ra0, rb0, 2);
;   __syncthreads();
;   ldf(0, 0, 0);
.LBB0_1461:
	s_or_b64 exec, exec, s[4:5]
	v_mov_b32_e32 v32, v172
	s_mov_b64 s[4:5], 0x10000
	v_ashrrev_i32_e32 v10, 3, v32
	v_lshlrev_b32_e32 v0, 3, v32
	v_and_b32_e32 v33, 56, v0
	v_lshl_add_u32 v2, s13, 7, v10
	v_lshlrev_b32_e32 v144, 1, v33
	v_ashrrev_i32_e32 v3, 31, v2
	v_add_u32_e32 v11, s14, v10
	v_lshl_add_u64 v[4:5], s[6:7], 0, v[144:145]
	v_lshlrev_b64 v[2:3], 11, v[2:3]
	v_lshl_add_u64 v[154:155], v[4:5], 0, v[2:3]
	v_min_i32_e32 v2, 0x801f, v11
	v_ashrrev_i32_e32 v3, 31, v2
	v_lshl_add_u64 v[0:1], s[56:57], 0, v[144:145]
	v_lshlrev_b64 v[2:3], 11, v[2:3]
	v_lshl_add_u64 v[8:9], v[0:1], 0, v[2:3]
	v_min_i32_e32 v2, 0x7fff, v11
	v_ashrrev_i32_e32 v3, 31, v2
	v_min_i32_e32 v6, 0x803f, v11
	v_lshlrev_b64 v[2:3], 11, v[2:3]
	v_ashrrev_i32_e32 v7, 31, v6
	v_lshl_add_u64 v[16:17], v[0:1], 0, v[2:3]
	v_min_i32_e32 v2, 0x7fdf, v11
	v_lshlrev_b64 v[6:7], 11, v[6:7]
	v_ashrrev_i32_e32 v3, 31, v2
	v_lshl_add_u64 v[152:153], v[0:1], 0, v[6:7]
	v_lshlrev_b64 v[2:3], 11, v[2:3]
	v_lshl_add_u64 v[24:25], v[0:1], 0, v[2:3]
	global_load_dwordx4 v[0:3], v[152:153], off
	v_lshl_add_u64 v[156:157], v[8:9], 0, s[4:5]
	v_lshl_add_u64 v[158:159], v[154:155], 0, s[4:5]
	s_mov_b64 s[4:5], 0x20000
	v_lshl_add_u64 v[160:161], v[16:17], 0, s[4:5]
	v_lshl_add_u64 v[162:163], v[154:155], 0, s[4:5]
	s_mov_b64 s[4:5], 0x30000
	v_lshl_add_u64 v[164:165], v[24:25], 0, s[4:5]
	v_lshl_add_u64 v[166:167], v[154:155], 0, s[4:5]
	s_movk_i32 s4, 0x48
	v_and_b32_e32 v34, 31, v32
	v_mul_lo_u32 v35, v10, s4
	global_load_dwordx4 v[4:7], v[154:155], off
	s_mov_b32 s15, 0x10000
	v_add_co_u32_e64 v8, s[4:5], s15, v8
	s_mov_b32 s14, 0
	s_nop 0
	v_addc_co_u32_e64 v9, s[4:5], 0, v9, s[4:5]
	global_load_dwordx4 v[8:11], v[8:9], off
	s_waitcnt vmcnt(19)
	v_add_co_u32_e64 v12, s[4:5], s15, v154
	s_nop 1
	v_addc_co_u32_e64 v13, s[4:5], 0, v155, s[4:5]
	global_load_dwordx4 v[12:15], v[12:13], off
	s_mov_b32 s15, 0x20000
	v_add_co_u32_e64 v16, s[4:5], s15, v16
	s_nop 1
	v_addc_co_u32_e64 v17, s[4:5], 0, v17, s[4:5]
	global_load_dwordx4 v[16:19], v[16:17], off
	v_add_co_u32_e64 v20, s[4:5], s15, v154
	s_nop 1
	v_addc_co_u32_e64 v21, s[4:5], 0, v155, s[4:5]
	global_load_dwordx4 v[20:23], v[20:21], off
	s_mov_b32 s15, 0x30000
	v_add_co_u32_e64 v24, s[4:5], s15, v24
	s_nop 1
	v_addc_co_u32_e64 v25, s[4:5], 0, v25, s[4:5]
	global_load_dwordx4 v[24:27], v[24:25], off
	v_add_co_u32_e64 v28, s[4:5], s15, v154
	s_nop 1
	v_addc_co_u32_e64 v29, s[4:5], 0, v155, s[4:5]
	global_load_dwordx4 v[28:31], v[28:29], off
	s_nop 0
	global_load_dwordx4 v[64:67], v[152:153], off offset:128
	global_load_dwordx4 v[68:71], v[154:155], off offset:128
	global_load_dwordx4 v[72:75], v[156:157], off offset:128
	global_load_dwordx4 v[76:79], v[158:159], off offset:128
	global_load_dwordx4 v[80:83], v[160:161], off offset:128
	global_load_dwordx4 v[84:87], v[162:163], off offset:128
	global_load_dwordx4 v[88:91], v[164:165], off offset:128
	global_load_dwordx4 v[92:95], v[166:167], off offset:128
	v_lshrrev_b32_e32 v204, 3, v172
	v_and_b32_e32 v205, 7, v172
	v_bfe_u32 v144, v204, 1, 3
	v_xor_b32_e32 v144, v144, v205
	v_lshlrev_b32_e32 v144, 4, v144
	v_lshl_or_b32 v144, v204, 7, v144
	s_waitcnt vmcnt(15)
	ds_write_b128 v144, v[0:3] offset:0
	s_waitcnt vmcnt(14)
	ds_write_b128 v144, v[4:7] offset:16384
	s_waitcnt vmcnt(13)
	ds_write_b128 v144, v[8:11] offset:4096
	s_waitcnt vmcnt(12)
	ds_write_b128 v144, v[12:15] offset:20480
	s_waitcnt vmcnt(11)
	ds_write_b128 v144, v[16:19] offset:8192
	s_waitcnt vmcnt(10)
	ds_write_b128 v144, v[20:23] offset:24576
	s_waitcnt vmcnt(9)
	ds_write_b128 v144, v[24:27] offset:12288
	s_waitcnt vmcnt(8)
	ds_write_b128 v144, v[28:31] offset:28672
	global_load_dwordx4 v[96:99], v[152:153], off offset:256
	global_load_dwordx4 v[100:103], v[154:155], off offset:256
	global_load_dwordx4 v[104:107], v[156:157], off offset:256
	global_load_dwordx4 v[108:111], v[158:159], off offset:256
	global_load_dwordx4 v[112:115], v[160:161], off offset:256
	global_load_dwordx4 v[116:119], v[162:163], off offset:256
	global_load_dwordx4 v[120:123], v[164:165], off offset:256
	global_load_dwordx4 v[124:127], v[166:167], off offset:256
	v_lshrrev_b32_e32 v0, 1, v32
	v_and_or_b32 v1, v0, s72, v34
	v_and_b32_e32 v0, 16, v0
	s_movk_i32 s4, 0x90
	v_mad_u64_u32 v[168:169], s[4:5], v1, s4, v[0:1]
	v_and_b32_e32 v1, 0x5f, v32
	v_mul_u32_u24_e32 v1, 0x48, v1
	v_lshl_add_u32 v169, v1, 1, v0
	v_and_b32_e32 v204, 15, v172
	v_bfe_u32 v205, v172, 4, 2
	v_lshrrev_b32_e32 v206, 1, v204
	v_xor_b32_e32 v205, v205, v206
	v_lshlrev_b32_e32 v205, 4, v205
	v_lshl_or_b32 v204, v204, 7, v205
	v_lshrrev_b32_e32 v206, 7, v172
	v_lshl_add_u32 v168, v206, 13, v204
	v_bfe_u32 v206, v172, 6, 1
	v_lshl_add_u32 v169, v206, 13, v204
	v_add_u32_e32 v169, 0x4000, v169
	v_xor_b32_e32 v220, 64, v168
	v_xor_b32_e32 v221, 64, v169
	s_waitcnt lgkmcnt(0)
	s_barrier
	ds_read_b128 v[128:131], v168 offset:0
	ds_read_b128 v[132:135], v168 offset:2048
	ds_read_b128 v[136:139], v168 offset:4096
	ds_read_b128 v[140:143], v168 offset:6144
	ds_read_b128 v[188:191], v169 offset:0
	ds_read_b128 v[192:195], v169 offset:2048
	ds_read_b128 v[196:199], v169 offset:4096
	ds_read_b128 v[200:203], v169 offset:6144
	v_mov_b32_e32 v0, 0
	v_add_u32_e32 v171, 0x9000, v144
	v_mov_b32_e32 v1, v0
	v_mov_b32_e32 v2, v0
	v_mov_b32_e32 v3, v0
	v_mov_b32_e32 v4, v0
	v_mov_b32_e32 v5, v0
	v_mov_b32_e32 v6, v0
	v_mov_b32_e32 v7, v0
	v_mov_b32_e32 v8, v0
	v_mov_b32_e32 v9, v0
	v_mov_b32_e32 v10, v0
	v_mov_b32_e32 v11, v0
	v_mov_b32_e32 v12, v0
	v_mov_b32_e32 v13, v0
	v_mov_b32_e32 v14, v0
	v_mov_b32_e32 v15, v0
	v_mov_b32_e32 v16, v0
	v_mov_b32_e32 v17, v0
	v_mov_b32_e32 v18, v0
	v_mov_b32_e32 v19, v0
	v_mov_b32_e32 v20, v0
	v_mov_b32_e32 v21, v0
	v_mov_b32_e32 v22, v0
	v_mov_b32_e32 v23, v0
	v_mov_b32_e32 v24, v0
	v_mov_b32_e32 v25, v0
	v_mov_b32_e32 v26, v0
	v_mov_b32_e32 v27, v0
	v_mov_b32_e32 v28, v0
	v_mov_b32_e32 v29, v0
	v_mov_b32_e32 v30, v0
	v_mov_b32_e32 v31, v0
	v_mov_b32_e32 v32, v0
	v_mov_b32_e32 v33, v0
	v_mov_b32_e32 v34, v0
	v_mov_b32_e32 v35, v0
	v_mov_b32_e32 v36, v0
	v_mov_b32_e32 v37, v0
	v_mov_b32_e32 v38, v0
	v_mov_b32_e32 v39, v0
	v_mov_b32_e32 v40, v0
	v_mov_b32_e32 v41, v0
	v_mov_b32_e32 v42, v0
	v_mov_b32_e32 v43, v0
	v_mov_b32_e32 v44, v0
	v_mov_b32_e32 v45, v0
	v_mov_b32_e32 v46, v0
	v_mov_b32_e32 v47, v0
	v_mov_b32_e32 v48, v0
	v_mov_b32_e32 v49, v0
	v_mov_b32_e32 v50, v0
	v_mov_b32_e32 v51, v0
	v_mov_b32_e32 v52, v0
	v_mov_b32_e32 v53, v0
	v_mov_b32_e32 v54, v0
	v_mov_b32_e32 v55, v0
	v_mov_b32_e32 v56, v0
	v_mov_b32_e32 v57, v0
	v_mov_b32_e32 v58, v0
	v_mov_b32_e32 v59, v0
	v_mov_b32_e32 v60, v0
	v_mov_b32_e32 v61, v0
	v_mov_b32_e32 v62, v0
	v_mov_b32_e32 v63, v0
; #define MFMA32(a, b, c) __builtin_amdgcn_mfma_f32_32x32x16_bf16((a), (b), (c), 0, 0, 0)
; #define SB_ __builtin_amdgcn_sched_barrier(0)
; template <bool SWAP, bool HALF>
; DI void gemm_mainloop(const GemmDesc& d, int m0, int n0, bf16_t* smem, f32x16 (&acc)[2][2], int dry) {
;     ...
;   auto lw = [&](const u32x4 (&ra)[4], const u32x4 (&rb)[4], int buf) {
;     bf16_t* An = smem + buf * 2 * TILE_EL + lds_w; bf16_t* Bn = An + TILE_EL;
; #pragma unroll
;     for (int i = 0; i < 4; ++i) {
;       *(u32x4*)(An + 32 * i * LST) = ra[i];
;       *(u32x4*)(Bn + 32 * i * LST) = rb[i];
;     }
;   };
;   bf16x8 fa[2][2], fb[2][2];
;   auto ldf = [&](int buf, int kk, int set) {
;     const bf16_t* Ab = smem + buf * 2 * TILE_EL + ((HALF ? 0 : wm * 64) + r) * LST + 8 * hh + kk * 16;
;     const bf16_t* Bb = smem + buf * 2 * TILE_EL + TILE_EL + ((HALF ? w * 32 : wn * 64) + r) * LST + 8 * hh + kk * 16;
; #pragma unroll
;     for (int i = 0; i < 2; ++i) { fa[set][i] = *(const bf16x8*)(Ab + i * 32 * LST); if (!HALF || i == 0) fb[set][i] = *(const bf16x8*)(Bb + i * 32 * LST); }
;   };
;   auto mma = [&](int set) {
; #pragma unroll
;     for (int a = 0; a < 2; ++a)
; #pragma unroll
;       for (int b = 0; b < (HALF ? 1 : 2); ++b) {
;         if (SWAP) acc[a][b] = MFMA32(fb[set][b], fa[set][a], acc[a][b]);
;         else      acc[a][b] = MFMA32(fa[set][a], fb[set][b], acc[a][b]);
;       }
;   };
;     ...
;   auto stage = [&](int cur, u32x4 (&ran)[4], u32x4 (&rbn)[4], int ks) {
;     ldf(cur, 1, 1); SB_;
;     mma(0); SB_;
;     ldf(cur, 2, 0); SB_;
;     lw(ran, rbn, cur ^ 1);
;     gl(ran, rbn, (ks + 3 < nk) ? ks + 3 : nk - 1);
;     SB_;
;     mma(1); SB_;
;     __syncthreads();
;     ldf(cur, 3, 1); SB_;
;     mma(0); SB_;
;     ldf(cur ^ 1, 0, 0);
;     SB_;
;     mma(1); SB_;
;     __syncthreads();
;   };
.LBB0_1462:
	ds_read_b128 v[204:207], v220 offset:0
	ds_read_b128 v[208:211], v220 offset:2048
	ds_read_b128 v[212:215], v220 offset:4096
	ds_read_b128 v[216:219], v220 offset:6144
	ds_read_b128 v[232:235], v221 offset:0
	ds_read_b128 v[236:239], v221 offset:2048
	ds_read_b128 v[240:243], v221 offset:4096
	ds_read_b128 v[244:247], v221 offset:6144
	s_min_u32 s4, s14, 12
	s_lshl_b32 s4, s4, 7
	s_add_i32 s18, s4, 0x180
	s_waitcnt lgkmcnt(8)
	v_mfma_f32_16x16x32_bf16 v[0:3], v[188:191], v[128:131], v[0:3]
	v_mfma_f32_16x16x32_bf16 v[4:7], v[192:195], v[128:131], v[4:7]
	s_waitcnt vmcnt(15)
	ds_write_b128 v144, v[64:67] offset:32768
	v_mfma_f32_16x16x32_bf16 v[8:11], v[196:199], v[128:131], v[8:11]
	v_mfma_f32_16x16x32_bf16 v[12:15], v[200:203], v[128:131], v[12:15]
	s_waitcnt vmcnt(14)
	ds_write_b128 v144, v[68:71] offset:49152
	v_mfma_f32_16x16x32_bf16 v[16:19], v[188:191], v[132:135], v[16:19]
	v_mfma_f32_16x16x32_bf16 v[20:23], v[192:195], v[132:135], v[20:23]
	s_waitcnt vmcnt(13)
	ds_write_b128 v144, v[72:75] offset:36864
	v_mfma_f32_16x16x32_bf16 v[24:27], v[196:199], v[132:135], v[24:27]
	v_mfma_f32_16x16x32_bf16 v[28:31], v[200:203], v[132:135], v[28:31]
	s_waitcnt vmcnt(12)
	ds_write_b128 v144, v[76:79] offset:53248
	v_mfma_f32_16x16x32_bf16 v[32:35], v[188:191], v[136:139], v[32:35]
	v_mfma_f32_16x16x32_bf16 v[36:39], v[192:195], v[136:139], v[36:39]
	s_waitcnt vmcnt(11)
	ds_write_b128 v144, v[80:83] offset:40960
	v_mfma_f32_16x16x32_bf16 v[40:43], v[196:199], v[136:139], v[40:43]
	v_mfma_f32_16x16x32_bf16 v[44:47], v[200:203], v[136:139], v[44:47]
	s_waitcnt vmcnt(10)
	ds_write_b128 v144, v[84:87] offset:57344
	v_mfma_f32_16x16x32_bf16 v[48:51], v[188:191], v[140:143], v[48:51]
	v_mfma_f32_16x16x32_bf16 v[52:55], v[192:195], v[140:143], v[52:55]
	s_waitcnt vmcnt(9)
	ds_write_b128 v144, v[88:91] offset:45056
	v_mfma_f32_16x16x32_bf16 v[56:59], v[196:199], v[140:143], v[56:59]
	v_mfma_f32_16x16x32_bf16 v[60:63], v[200:203], v[140:143], v[60:63]
	s_waitcnt vmcnt(8)
	ds_write_b128 v144, v[92:95] offset:61440
	s_waitcnt lgkmcnt(0)
	s_barrier
	ds_read_b128 v[128:131], v168 offset:32768
	ds_read_b128 v[132:135], v168 offset:34816
	ds_read_b128 v[136:139], v168 offset:36864
	ds_read_b128 v[140:143], v168 offset:38912
	ds_read_b128 v[188:191], v169 offset:32768
	ds_read_b128 v[192:195], v169 offset:34816
	ds_read_b128 v[196:199], v169 offset:36864
	ds_read_b128 v[200:203], v169 offset:38912
	v_mfma_f32_16x16x32_bf16 v[0:3], v[232:235], v[204:207], v[0:3]
	v_mfma_f32_16x16x32_bf16 v[4:7], v[236:239], v[204:207], v[4:7]
	v_lshl_add_u64 v[64:65], v[152:153], 0, s[18:19]
	global_load_dwordx4 v[64:67], v[64:65], off
	v_mfma_f32_16x16x32_bf16 v[8:11], v[240:243], v[204:207], v[8:11]
	v_mfma_f32_16x16x32_bf16 v[12:15], v[244:247], v[204:207], v[12:15]
	v_lshl_add_u64 v[68:69], v[154:155], 0, s[18:19]
	global_load_dwordx4 v[68:71], v[68:69], off
	v_mfma_f32_16x16x32_bf16 v[16:19], v[232:235], v[208:211], v[16:19]
	v_mfma_f32_16x16x32_bf16 v[20:23], v[236:239], v[208:211], v[20:23]
	v_lshl_add_u64 v[72:73], v[156:157], 0, s[18:19]
	global_load_dwordx4 v[72:75], v[72:73], off
	v_mfma_f32_16x16x32_bf16 v[24:27], v[240:243], v[208:211], v[24:27]
	v_mfma_f32_16x16x32_bf16 v[28:31], v[244:247], v[208:211], v[28:31]
	v_lshl_add_u64 v[76:77], v[158:159], 0, s[18:19]
	global_load_dwordx4 v[76:79], v[76:77], off
	v_mfma_f32_16x16x32_bf16 v[32:35], v[232:235], v[212:215], v[32:35]
	v_mfma_f32_16x16x32_bf16 v[36:39], v[236:239], v[212:215], v[36:39]
	v_lshl_add_u64 v[80:81], v[160:161], 0, s[18:19]
	global_load_dwordx4 v[80:83], v[80:81], off
	v_mfma_f32_16x16x32_bf16 v[40:43], v[240:243], v[212:215], v[40:43]
	v_mfma_f32_16x16x32_bf16 v[44:47], v[244:247], v[212:215], v[44:47]
	v_lshl_add_u64 v[84:85], v[162:163], 0, s[18:19]
	global_load_dwordx4 v[84:87], v[84:85], off
	v_mfma_f32_16x16x32_bf16 v[48:51], v[232:235], v[216:219], v[48:51]
	v_mfma_f32_16x16x32_bf16 v[52:55], v[236:239], v[216:219], v[52:55]
	v_lshl_add_u64 v[88:89], v[164:165], 0, s[18:19]
	global_load_dwordx4 v[88:91], v[88:89], off
	v_mfma_f32_16x16x32_bf16 v[56:59], v[240:243], v[216:219], v[56:59]
	v_mfma_f32_16x16x32_bf16 v[60:63], v[244:247], v[216:219], v[60:63]
	v_lshl_add_u64 v[92:93], v[166:167], 0, s[18:19]
	global_load_dwordx4 v[92:95], v[92:93], off
	s_waitcnt lgkmcnt(0)
	s_barrier
	ds_read_b128 v[204:207], v220 offset:32768
	ds_read_b128 v[208:211], v220 offset:34816
	ds_read_b128 v[212:215], v220 offset:36864
	ds_read_b128 v[216:219], v220 offset:38912
	ds_read_b128 v[232:235], v221 offset:32768
	ds_read_b128 v[236:239], v221 offset:34816
	ds_read_b128 v[240:243], v221 offset:36864
	ds_read_b128 v[244:247], v221 offset:38912
	s_min_u32 s4, s14, 11
	s_lshl_b32 s4, s4, 7
	s_add_i32 s18, s4, 0x200
	s_waitcnt lgkmcnt(8)
	v_mfma_f32_16x16x32_bf16 v[0:3], v[188:191], v[128:131], v[0:3]
	v_mfma_f32_16x16x32_bf16 v[4:7], v[192:195], v[128:131], v[4:7]
	s_waitcnt vmcnt(15)
	ds_write_b128 v144, v[96:99] offset:0
	v_mfma_f32_16x16x32_bf16 v[8:11], v[196:199], v[128:131], v[8:11]
	v_mfma_f32_16x16x32_bf16 v[12:15], v[200:203], v[128:131], v[12:15]
	s_waitcnt vmcnt(14)
	ds_write_b128 v144, v[100:103] offset:16384
	v_mfma_f32_16x16x32_bf16 v[16:19], v[188:191], v[132:135], v[16:19]
	v_mfma_f32_16x16x32_bf16 v[20:23], v[192:195], v[132:135], v[20:23]
	s_waitcnt vmcnt(13)
	ds_write_b128 v144, v[104:107] offset:4096
	v_mfma_f32_16x16x32_bf16 v[24:27], v[196:199], v[132:135], v[24:27]
	v_mfma_f32_16x16x32_bf16 v[28:31], v[200:203], v[132:135], v[28:31]
	s_waitcnt vmcnt(12)
	ds_write_b128 v144, v[108:111] offset:20480
	v_mfma_f32_16x16x32_bf16 v[32:35], v[188:191], v[136:139], v[32:35]
	v_mfma_f32_16x16x32_bf16 v[36:39], v[192:195], v[136:139], v[36:39]
	s_waitcnt vmcnt(11)
	ds_write_b128 v144, v[112:115] offset:8192
	v_mfma_f32_16x16x32_bf16 v[40:43], v[196:199], v[136:139], v[40:43]
	v_mfma_f32_16x16x32_bf16 v[44:47], v[200:203], v[136:139], v[44:47]
	s_waitcnt vmcnt(10)
	ds_write_b128 v144, v[116:119] offset:24576
	v_mfma_f32_16x16x32_bf16 v[48:51], v[188:191], v[140:143], v[48:51]
	v_mfma_f32_16x16x32_bf16 v[52:55], v[192:195], v[140:143], v[52:55]
	s_waitcnt vmcnt(9)
	ds_write_b128 v144, v[120:123] offset:12288
	v_mfma_f32_16x16x32_bf16 v[56:59], v[196:199], v[140:143], v[56:59]
	v_mfma_f32_16x16x32_bf16 v[60:63], v[200:203], v[140:143], v[60:63]
	s_waitcnt vmcnt(8)
	ds_write_b128 v144, v[124:127] offset:28672
	s_waitcnt lgkmcnt(0)
	s_barrier
; DI float ssq_f(u64 v) { return (float)v * (1.f / 1048576.f); }
; #define SB_ __builtin_amdgcn_sched_barrier(0)
; template <bool SWAP, bool HALF>
; DI void gemm_mainloop(const GemmDesc& d, int m0, int n0, bf16_t* smem, f32x16 (&acc)[2][2], int dry) {
;     ...
;   auto stage = [&](int cur, u32x4 (&ran)[4], u32x4 (&rbn)[4], int ks) {
;     ldf(cur, 1, 1); SB_;
;     mma(0); SB_;
;     ldf(cur, 2, 0); SB_;
;     lw(ran, rbn, cur ^ 1);
;     gl(ran, rbn, (ks + 3 < nk) ? ks + 3 : nk - 1);
;     SB_;
;     mma(1); SB_;
;     __syncthreads();
;     ldf(cur, 3, 1); SB_;
;     mma(0); SB_;
;     ldf(cur ^ 1, 0, 0);
;     SB_;
;     mma(1); SB_;
;     __syncthreads();
;   };
;   gl(ra0, rb0, 0);
;   gl(ra1, rb1, 1);
;   lw(ra0, rb0, 0);
;   gl(ra0, rb0, 2);
;   __syncthreads();
;   ldf(0, 0, 0);
; #pragma unroll 1
;   for (int ks = 0; ks < nk; ks += 2) {
;     stage(0, ra1, rb1, ks);
;     stage(1, ra0, rb0, ks + 1);
;   }
; DI void gemm_tile(const GemmDesc& d, int m0, int n0, bf16_t* smem, int dry) {
;     ...
;   } else if (t < 128) {
;     rs_s[t] = rsqrtf(ssq_f(myss) * d.inv_dim + EPS);
;   }
;   if (half) {
; #pragma unroll
;     for (int a = 0; a < 2; ++a)
; #pragma unroll
;       for (int g = 0; g < 4; ++g) {
;         f32x4 o;
; #pragma unroll
;         for (int j = 0; j < 4; ++j) o[j] = acc[a][0][4 * g + j];
;         *(f32x4*)(Ct + (a * 32 + r) * CS + w * 32 + 8 * g + 4 * hh) = o;
;       }
;   } else {
; #pragma unroll
;     for (int a = 0; a < 2; ++a)
; #pragma unroll
;       for (int b = 0; b < 2; ++b)
; #pragma unroll
;         for (int g = 0; g < 4; ++g) {
;           f32x4 o;
; #pragma unroll
;           for (int j = 0; j < 4; ++j) o[j] = acc[a][b][4 * g + j];
;           *(f32x4*)(Ct + (wm * 64 + a * 32 + r) * CS + wn * 64 + b * 32 + 8 * g + 4 * hh) = o;
;         }
;   }
;   __syncthreads();
	ds_read_b128 v[128:131], v168 offset:0
	ds_read_b128 v[132:135], v168 offset:2048
	ds_read_b128 v[136:139], v168 offset:4096
	ds_read_b128 v[140:143], v168 offset:6144
	ds_read_b128 v[188:191], v169 offset:0
	ds_read_b128 v[192:195], v169 offset:2048
	ds_read_b128 v[196:199], v169 offset:4096
	ds_read_b128 v[200:203], v169 offset:6144
	v_mfma_f32_16x16x32_bf16 v[0:3], v[232:235], v[204:207], v[0:3]
	v_mfma_f32_16x16x32_bf16 v[4:7], v[236:239], v[204:207], v[4:7]
	v_lshl_add_u64 v[96:97], v[152:153], 0, s[18:19]
	global_load_dwordx4 v[96:99], v[96:97], off
	v_mfma_f32_16x16x32_bf16 v[8:11], v[240:243], v[204:207], v[8:11]
	v_mfma_f32_16x16x32_bf16 v[12:15], v[244:247], v[204:207], v[12:15]
	v_lshl_add_u64 v[100:101], v[154:155], 0, s[18:19]
	global_load_dwordx4 v[100:103], v[100:101], off
	v_mfma_f32_16x16x32_bf16 v[16:19], v[232:235], v[208:211], v[16:19]
	v_mfma_f32_16x16x32_bf16 v[20:23], v[236:239], v[208:211], v[20:23]
	v_lshl_add_u64 v[104:105], v[156:157], 0, s[18:19]
	global_load_dwordx4 v[104:107], v[104:105], off
	v_mfma_f32_16x16x32_bf16 v[24:27], v[240:243], v[208:211], v[24:27]
	v_mfma_f32_16x16x32_bf16 v[28:31], v[244:247], v[208:211], v[28:31]
	v_lshl_add_u64 v[108:109], v[158:159], 0, s[18:19]
	global_load_dwordx4 v[108:111], v[108:109], off
	v_mfma_f32_16x16x32_bf16 v[32:35], v[232:235], v[212:215], v[32:35]
	v_mfma_f32_16x16x32_bf16 v[36:39], v[236:239], v[212:215], v[36:39]
	v_lshl_add_u64 v[112:113], v[160:161], 0, s[18:19]
	global_load_dwordx4 v[112:115], v[112:113], off
	v_mfma_f32_16x16x32_bf16 v[40:43], v[240:243], v[212:215], v[40:43]
	v_mfma_f32_16x16x32_bf16 v[44:47], v[244:247], v[212:215], v[44:47]
	v_lshl_add_u64 v[116:117], v[162:163], 0, s[18:19]
	global_load_dwordx4 v[116:119], v[116:117], off
	v_mfma_f32_16x16x32_bf16 v[48:51], v[232:235], v[216:219], v[48:51]
	v_mfma_f32_16x16x32_bf16 v[52:55], v[236:239], v[216:219], v[52:55]
	v_lshl_add_u64 v[120:121], v[164:165], 0, s[18:19]
	global_load_dwordx4 v[120:123], v[120:121], off
	v_mfma_f32_16x16x32_bf16 v[56:59], v[240:243], v[216:219], v[56:59]
	v_mfma_f32_16x16x32_bf16 v[60:63], v[244:247], v[216:219], v[60:63]
	v_lshl_add_u64 v[124:125], v[166:167], 0, s[18:19]
	global_load_dwordx4 v[124:127], v[124:125], off
	s_add_i32 s4, s14, 2
	s_cmp_lt_u32 s14, 14
	s_mov_b32 s14, s4
	s_waitcnt lgkmcnt(0)
	s_barrier
	s_cbranch_scc1 .LBB0_1462
	s_and_saveexec_b64 s[4:5], vcc
	s_cbranch_execz .LBB0_1465
	s_mov_b32 s14, 0x800000
	s_waitcnt vmcnt(15)
	v_mul_f32_e32 v64, 0x4b800000, v170
	v_cmp_gt_f32_e32 vcc, s14, v170
	s_nop 1
	v_cndmask_b32_e32 v64, v170, v64, vcc
	v_rsq_f32_e32 v64, v64
	s_nop 0
	v_mul_f32_e32 v65, 0x45800000, v64
	v_cndmask_b32_e32 v64, v64, v65, vcc
	v_lshl_add_u32 v65, v150, 2, v181
	ds_write_b32 v65, v64
.LBB0_1465:
	s_or_b64 exec, exec, s[4:5]
	s_waitcnt vmcnt(15)
	v_and_b32_e32 v64, 31, v150
	v_lshrrev_b32_e32 v65, 1, v150
	v_and_or_b32 v66, v65, s72, v64
	v_lshlrev_b32_e32 v64, 2, v150
	v_and_b32_e32 v65, 16, v65
	s_movk_i32 s4, 0x100
	v_and_or_b32 v64, v64, s4, v65
	v_mad_u64_u32 v[64:65], s[4:5], v66, s22, v[64:65]
	s_lshl_b32 s4, s13, 6
	s_ashr_i32 s5, s4, 31
	s_lshl_b64 s[4:5], s[4:5], 1
	v_and_b32_e32 v204, 15, v150
	v_lshrrev_b32_e32 v205, 1, v150
	v_and_or_b32 v204, v205, s72, v204
	v_lshlrev_b32_e32 v205, 2, v150
	v_and_b32_e32 v206, 0x30, v150
	v_and_b32_e32 v205, 0x100, v205
	v_or_b32_e32 v205, v205, v206
	v_mad_u32_u24 v64, v204, s22, v205
	ds_write_b128 v64, v[0:3]
	ds_write_b128 v64, v[4:7] offset:64
	ds_write_b128 v64, v[8:11] offset:128
	ds_write_b128 v64, v[12:15] offset:192
	ds_write_b128 v64, v[16:19] offset:8448
	ds_write_b128 v64, v[20:23] offset:8512
	ds_write_b128 v64, v[24:27] offset:8576
	ds_write_b128 v64, v[28:31] offset:8640
	ds_write_b128 v64, v[32:35] offset:16896
	ds_write_b128 v64, v[36:39] offset:16960
	ds_write_b128 v64, v[40:43] offset:17024
	ds_write_b128 v64, v[44:47] offset:17088
	ds_write_b128 v64, v[48:51] offset:25344
	ds_write_b128 v64, v[52:55] offset:25408
	ds_write_b128 v64, v[56:59] offset:25472
	ds_write_b128 v64, v[60:63] offset:25536
	s_add_u32 s4, s68, s4
	v_lshlrev_b32_e32 v0, 3, v150
	s_addc_u32 s5, s69, s5
	v_and_b32_e32 v144, 0x78, v0
	s_add_i32 s11, s11, s10
	v_lshl_add_u64 v[0:1], s[4:5], 0, v[144:145]
	s_sub_i32 s4, s11, s12
	v_ashrrev_i32_e32 v4, 4, v150
	v_lshlrev_b32_e32 v3, 5, v150
	v_and_b32_e32 v5, 7, v150
	s_lshl_b32 s4, s4, 10
	v_mul_lo_u32 v2, v4, s22
	v_and_b32_e32 v3, 0x100, v3
	v_lshlrev_b32_e32 v5, 4, v5
	s_or_b32 s4, s4, s29
	v_add3_u32 v2, v2, v3, v5
	v_lshlrev_b32_e32 v3, 2, v4
	v_add_u32_e32 v4, s4, v4
	s_mov_b32 s10, 8
	s_waitcnt lgkmcnt(0)
	s_barrier
	s_branch .LBB0_1467

; DI int otid() { int t = threadIdx.x; asm volatile("" : "+v"(t)); return t; }
; template <bool SWAP, bool HALF>
; DI void gemm_mainloop(const GemmDesc& d, int m0, int n0, bf16_t* smem, f32x16 (&acc)[2][2], int dry) {
;   const int t = otid(), lane = t & 63, w = t >> 6, wm = w >> 1, wn = w & 1, r = lane & 31, hh = lane >> 5;
;   const int lrow = t >> 3, lkc = t & 7;
;   const bf16_t* ap[4]; const bf16_t* bp[4];
; #pragma unroll
;   for (int i = 0; i < 4; ++i) {
;     int am = m0 + lrow + 32 * i; am = am < M ? am : M - 1;
;     ap[i] = d.A + (size_t)am * d.lda + lkc * 8 + (d.a_grp ? (n0 / d.a_grp) * d.a_grp : 0);
;     bp[i] = d.Bt + (size_t)(n0 + lrow + 32 * i) * d.ldb + lkc * 8;
;   }
; #pragma unroll
;   for (int a = 0; a < 2; ++a)
; #pragma unroll
;     for (int b = 0; b < 2; ++b)
; #pragma unroll
;       for (int i = 0; i < 16; ++i) acc[a][b][i] = 0.f;
;   u32x4 ra0[4], rb0[4], ra1[4], rb1[4];
;   const int nk = d.K >> 6;
;   const int lds_w = lrow * LST + lkc * 8;
;     ...
;   gl(ra0, rb0, 0);
;   gl(ra1, rb1, 1);
;   lw(ra0, rb0, 0);
;   gl(ra0, rb0, 2);
;   __syncthreads();
;   ldf(0, 0, 0);
.LBB0_1527:
	s_lshr_b32 s1, s12, 3
	s_and_b32 s1, s1, 0xffffff8
	v_readlane_b32 s4, v228, 38
	s_sub_i32 s4, s4, s1
	s_min_i32 s4, s4, 8
	s_abs_i32 s5, s4
	v_cvt_f32_u32_e32 v0, s5
	s_sub_i32 s14, 0, s5
	s_lshl_b32 s10, s1, 3
	s_sub_i32 s10, s12, s10
	v_rcp_iflag_f32_e32 v0, v0
	s_abs_i32 s13, s10
	s_xor_b32 s11, s10, s4
	s_ashr_i32 s11, s11, 31
	v_mul_f32_e32 v0, 0x4f7ffffe, v0
	v_cvt_u32_f32_e32 v0, v0
	v_mov_b32_e32 v150, v172
	v_mov_b32_e32 v32, v172
	v_readfirstlane_b32 s15, v0
	s_mul_i32 s14, s14, s15
	s_mul_hi_u32 s14, s15, s14
	s_add_i32 s15, s15, s14
	s_mul_hi_u32 s14, s13, s15
	s_mul_i32 s15, s14, s5
	s_sub_i32 s13, s13, s15
	s_add_i32 s16, s14, 1
	s_sub_i32 s15, s13, s5
	s_cmp_ge_u32 s13, s5
	s_cselect_b32 s14, s16, s14
	s_cselect_b32 s13, s15, s13
	s_add_i32 s15, s14, 1
	s_cmp_ge_u32 s13, s5
	s_cselect_b32 s5, s15, s14
	s_xor_b32 s5, s5, s11
	s_sub_i32 s11, s5, s11
	s_mul_i32 s4, s11, s4
	s_sub_i32 s4, s10, s4
	s_add_i32 s1, s1, s4
	s_lshl_b32 s1, s1, 10
	s_or_b32 s13, s1, s29
	v_lshlrev_b32_e32 v0, 3, v32
	v_ashrrev_i32_e32 v8, 3, v32
	v_and_b32_e32 v33, 56, v0
	v_add_u32_e32 v9, s13, v8
	v_lshlrev_b32_e32 v144, 1, v33
	v_lshl_add_u64 v[4:5], s[68:69], 0, v[144:145]
	v_min_i32_e32 v0, 0x803f, v9
	v_mad_i64_i32 v[152:153], s[4:5], v0, s26, v[4:5]
	global_load_dwordx4 v[0:3], v[152:153], off
	s_lshl_b32 s4, s11, 7
	v_min_i32_e32 v11, 0x801f, v9
	v_add_u32_e32 v10, s4, v8
	v_add_u32_e32 v11, 32, v11
	v_lshl_add_u64 v[6:7], s[6:7], 0, v[144:145]
	v_mad_i64_i32 v[156:157], s[10:11], v11, s26, v[4:5]
	v_add_u32_e32 v11, 32, v10
	v_mad_i64_i32 v[158:159], s[10:11], v11, s26, v[6:7]
	v_min_i32_e32 v11, 0x7fff, v9
	v_min_i32_e32 v9, 0x7fdf, v9
	v_add_u32_e32 v11, 64, v11
	v_add_u32_e32 v9, 0x60, v9
	v_mad_i64_i32 v[160:161], s[10:11], v11, s26, v[4:5]
	v_add_u32_e32 v11, 64, v10
	v_mad_i64_i32 v[164:165], s[10:11], v9, s26, v[4:5]
	v_add_u32_e32 v4, 0x60, v10
	s_movk_i32 s5, 0x48
	s_mov_b32 s1, 0
	v_mad_i64_i32 v[154:155], s[10:11], v10, s26, v[6:7]
	v_mad_i64_i32 v[162:163], s[10:11], v11, s26, v[6:7]
	v_mad_i64_i32 v[166:167], s[10:11], v4, s26, v[6:7]
	v_and_b32_e32 v34, 31, v32
	v_mul_lo_u32 v35, v8, s5
	global_load_dwordx4 v[4:7], v[154:155], off
	global_load_dwordx4 v[8:11], v[156:157], off
	global_load_dwordx4 v[12:15], v[158:159], off
	global_load_dwordx4 v[16:19], v[160:161], off
	global_load_dwordx4 v[20:23], v[162:163], off
	global_load_dwordx4 v[24:27], v[164:165], off
	global_load_dwordx4 v[28:31], v[166:167], off
	global_load_dwordx4 v[64:67], v[152:153], off offset:128
	global_load_dwordx4 v[68:71], v[154:155], off offset:128
	global_load_dwordx4 v[72:75], v[156:157], off offset:128
	global_load_dwordx4 v[76:79], v[158:159], off offset:128
	global_load_dwordx4 v[80:83], v[160:161], off offset:128
	global_load_dwordx4 v[84:87], v[162:163], off offset:128
	global_load_dwordx4 v[88:91], v[164:165], off offset:128
	global_load_dwordx4 v[92:95], v[166:167], off offset:128
	v_lshrrev_b32_e32 v204, 3, v172
	v_and_b32_e32 v205, 7, v172
	v_bfe_u32 v144, v204, 1, 3
	v_xor_b32_e32 v144, v144, v205
	v_lshlrev_b32_e32 v144, 4, v144
	v_lshl_or_b32 v144, v204, 7, v144
	s_waitcnt vmcnt(15)
	ds_write_b128 v144, v[0:3] offset:0
	s_waitcnt vmcnt(14)
	ds_write_b128 v144, v[4:7] offset:16384
	s_waitcnt vmcnt(13)
	ds_write_b128 v144, v[8:11] offset:4096
	s_waitcnt vmcnt(12)
	ds_write_b128 v144, v[12:15] offset:20480
	s_waitcnt vmcnt(11)
	ds_write_b128 v144, v[16:19] offset:8192
	s_waitcnt vmcnt(10)
	ds_write_b128 v144, v[20:23] offset:24576
	s_waitcnt vmcnt(9)
	ds_write_b128 v144, v[24:27] offset:12288
	s_waitcnt vmcnt(8)
	ds_write_b128 v144, v[28:31] offset:28672
	global_load_dwordx4 v[96:99], v[152:153], off offset:256
	global_load_dwordx4 v[100:103], v[154:155], off offset:256
	global_load_dwordx4 v[104:107], v[156:157], off offset:256
	global_load_dwordx4 v[108:111], v[158:159], off offset:256
	global_load_dwordx4 v[112:115], v[160:161], off offset:256
	global_load_dwordx4 v[116:119], v[162:163], off offset:256
	global_load_dwordx4 v[120:123], v[164:165], off offset:256
	global_load_dwordx4 v[124:127], v[166:167], off offset:256
	v_lshrrev_b32_e32 v0, 1, v32
	v_and_or_b32 v1, v0, s72, v34
	v_and_b32_e32 v0, 16, v0
	s_movk_i32 s5, 0x90
	v_mad_u64_u32 v[168:169], s[10:11], v1, s5, v[0:1]
	v_and_b32_e32 v1, 0x5f, v32
	v_mul_u32_u24_e32 v1, 0x48, v1
	v_lshl_add_u32 v169, v1, 1, v0
	v_and_b32_e32 v204, 15, v172
	v_bfe_u32 v205, v172, 4, 2
	v_lshrrev_b32_e32 v206, 1, v204
	v_xor_b32_e32 v205, v205, v206
	v_lshlrev_b32_e32 v205, 4, v205
	v_lshl_or_b32 v204, v204, 7, v205
	v_lshrrev_b32_e32 v206, 7, v172
	v_lshl_add_u32 v168, v206, 13, v204
	v_bfe_u32 v206, v172, 6, 1
	v_lshl_add_u32 v169, v206, 13, v204
	v_add_u32_e32 v169, 0x4000, v169
	v_xor_b32_e32 v220, 64, v168
	v_xor_b32_e32 v221, 64, v169
	s_waitcnt lgkmcnt(0)
	s_barrier
	ds_read_b128 v[128:131], v168 offset:0
	ds_read_b128 v[132:135], v168 offset:2048
	ds_read_b128 v[136:139], v168 offset:4096
	ds_read_b128 v[140:143], v168 offset:6144
	ds_read_b128 v[188:191], v169 offset:0
	ds_read_b128 v[192:195], v169 offset:2048
	ds_read_b128 v[196:199], v169 offset:4096
	ds_read_b128 v[200:203], v169 offset:6144
	v_mov_b32_e32 v0, 0
	v_add_u32_e32 v170, 0x9000, v144
	v_mov_b32_e32 v1, v0
	v_mov_b32_e32 v2, v0
	v_mov_b32_e32 v3, v0
	v_mov_b32_e32 v4, v0
	v_mov_b32_e32 v5, v0
	v_mov_b32_e32 v6, v0
	v_mov_b32_e32 v7, v0
	v_mov_b32_e32 v8, v0
	v_mov_b32_e32 v9, v0
	v_mov_b32_e32 v10, v0
	v_mov_b32_e32 v11, v0
	v_mov_b32_e32 v12, v0
	v_mov_b32_e32 v13, v0
	v_mov_b32_e32 v14, v0
	v_mov_b32_e32 v15, v0
	v_mov_b32_e32 v16, v0
	v_mov_b32_e32 v17, v0
	v_mov_b32_e32 v18, v0
	v_mov_b32_e32 v19, v0
	v_mov_b32_e32 v20, v0
	v_mov_b32_e32 v21, v0
	v_mov_b32_e32 v22, v0
	v_mov_b32_e32 v23, v0
	v_mov_b32_e32 v24, v0
	v_mov_b32_e32 v25, v0
	v_mov_b32_e32 v26, v0
	v_mov_b32_e32 v27, v0
	v_mov_b32_e32 v28, v0
	v_mov_b32_e32 v29, v0
	v_mov_b32_e32 v30, v0
	v_mov_b32_e32 v31, v0
	v_mov_b32_e32 v32, v0
	v_mov_b32_e32 v33, v0
	v_mov_b32_e32 v34, v0
	v_mov_b32_e32 v35, v0
	v_mov_b32_e32 v36, v0
	v_mov_b32_e32 v37, v0
	v_mov_b32_e32 v38, v0
	v_mov_b32_e32 v39, v0
	v_mov_b32_e32 v40, v0
	v_mov_b32_e32 v41, v0
	v_mov_b32_e32 v42, v0
	v_mov_b32_e32 v43, v0
	v_mov_b32_e32 v44, v0
	v_mov_b32_e32 v45, v0
	v_mov_b32_e32 v46, v0
	v_mov_b32_e32 v47, v0
	v_mov_b32_e32 v48, v0
	v_mov_b32_e32 v49, v0
	v_mov_b32_e32 v50, v0
	v_mov_b32_e32 v51, v0
	v_mov_b32_e32 v52, v0
	v_mov_b32_e32 v53, v0
	v_mov_b32_e32 v54, v0
	v_mov_b32_e32 v55, v0
	v_mov_b32_e32 v56, v0
	v_mov_b32_e32 v57, v0
	v_mov_b32_e32 v58, v0
	v_mov_b32_e32 v59, v0
	v_mov_b32_e32 v60, v0
	v_mov_b32_e32 v61, v0
	v_mov_b32_e32 v62, v0
	v_mov_b32_e32 v63, v0
; #define MFMA32(a, b, c) __builtin_amdgcn_mfma_f32_32x32x16_bf16((a), (b), (c), 0, 0, 0)
; #define SB_ __builtin_amdgcn_sched_barrier(0)
; template <bool SWAP, bool HALF>
; DI void gemm_mainloop(const GemmDesc& d, int m0, int n0, bf16_t* smem, f32x16 (&acc)[2][2], int dry) {
;     ...
;   auto lw = [&](const u32x4 (&ra)[4], const u32x4 (&rb)[4], int buf) {
;     bf16_t* An = smem + buf * 2 * TILE_EL + lds_w; bf16_t* Bn = An + TILE_EL;
; #pragma unroll
;     for (int i = 0; i < 4; ++i) {
;       *(u32x4*)(An + 32 * i * LST) = ra[i];
;       *(u32x4*)(Bn + 32 * i * LST) = rb[i];
;     }
;   };
;   bf16x8 fa[2][2], fb[2][2];
;   auto ldf = [&](int buf, int kk, int set) {
;     const bf16_t* Ab = smem + buf * 2 * TILE_EL + ((HALF ? 0 : wm * 64) + r) * LST + 8 * hh + kk * 16;
;     const bf16_t* Bb = smem + buf * 2 * TILE_EL + TILE_EL + ((HALF ? w * 32 : wn * 64) + r) * LST + 8 * hh + kk * 16;
; #pragma unroll
;     for (int i = 0; i < 2; ++i) { fa[set][i] = *(const bf16x8*)(Ab + i * 32 * LST); if (!HALF || i == 0) fb[set][i] = *(const bf16x8*)(Bb + i * 32 * LST); }
;   };
;   auto mma = [&](int set) {
; #pragma unroll
;     for (int a = 0; a < 2; ++a)
; #pragma unroll
;       for (int b = 0; b < (HALF ? 1 : 2); ++b) {
;         if (SWAP) acc[a][b] = MFMA32(fb[set][b], fa[set][a], acc[a][b]);
;         else      acc[a][b] = MFMA32(fa[set][a], fb[set][b], acc[a][b]);
;       }
;   };
;     ...
;   auto stage = [&](int cur, u32x4 (&ran)[4], u32x4 (&rbn)[4], int ks) {
;     ldf(cur, 1, 1); SB_;
;     mma(0); SB_;
;     ldf(cur, 2, 0); SB_;
;     lw(ran, rbn, cur ^ 1);
;     gl(ran, rbn, (ks + 3 < nk) ? ks + 3 : nk - 1);
;     SB_;
;     mma(1); SB_;
;     __syncthreads();
;     ldf(cur, 3, 1); SB_;
;     mma(0); SB_;
;     ldf(cur ^ 1, 0, 0);
;     SB_;
;     mma(1); SB_;
;     __syncthreads();
;   };
.LBB0_1528:
	ds_read_b128 v[204:207], v220 offset:0
	ds_read_b128 v[208:211], v220 offset:2048
	ds_read_b128 v[212:215], v220 offset:4096
	ds_read_b128 v[216:219], v220 offset:6144
	ds_read_b128 v[232:235], v221 offset:0
	ds_read_b128 v[236:239], v221 offset:2048
	ds_read_b128 v[240:243], v221 offset:4096
	ds_read_b128 v[244:247], v221 offset:6144
	s_min_u32 s5, s1, 40
	s_lshl_b32 s5, s5, 7
	s_add_i32 s18, s5, 0x180
	s_waitcnt lgkmcnt(8)
	v_mfma_f32_16x16x32_bf16 v[0:3], v[188:191], v[128:131], v[0:3]
	v_mfma_f32_16x16x32_bf16 v[4:7], v[192:195], v[128:131], v[4:7]
	s_waitcnt vmcnt(15)
	ds_write_b128 v144, v[64:67] offset:32768
	v_mfma_f32_16x16x32_bf16 v[8:11], v[196:199], v[128:131], v[8:11]
	v_mfma_f32_16x16x32_bf16 v[12:15], v[200:203], v[128:131], v[12:15]
	s_waitcnt vmcnt(14)
	ds_write_b128 v144, v[68:71] offset:49152
	v_mfma_f32_16x16x32_bf16 v[16:19], v[188:191], v[132:135], v[16:19]
	v_mfma_f32_16x16x32_bf16 v[20:23], v[192:195], v[132:135], v[20:23]
	s_waitcnt vmcnt(13)
	ds_write_b128 v144, v[72:75] offset:36864
	v_mfma_f32_16x16x32_bf16 v[24:27], v[196:199], v[132:135], v[24:27]
	v_mfma_f32_16x16x32_bf16 v[28:31], v[200:203], v[132:135], v[28:31]
	s_waitcnt vmcnt(12)
	ds_write_b128 v144, v[76:79] offset:53248
	v_mfma_f32_16x16x32_bf16 v[32:35], v[188:191], v[136:139], v[32:35]
	v_mfma_f32_16x16x32_bf16 v[36:39], v[192:195], v[136:139], v[36:39]
	s_waitcnt vmcnt(11)
	ds_write_b128 v144, v[80:83] offset:40960
	v_mfma_f32_16x16x32_bf16 v[40:43], v[196:199], v[136:139], v[40:43]
	v_mfma_f32_16x16x32_bf16 v[44:47], v[200:203], v[136:139], v[44:47]
	s_waitcnt vmcnt(10)
	ds_write_b128 v144, v[84:87] offset:57344
	v_mfma_f32_16x16x32_bf16 v[48:51], v[188:191], v[140:143], v[48:51]
	v_mfma_f32_16x16x32_bf16 v[52:55], v[192:195], v[140:143], v[52:55]
	s_waitcnt vmcnt(9)
	ds_write_b128 v144, v[88:91] offset:45056
	v_mfma_f32_16x16x32_bf16 v[56:59], v[196:199], v[140:143], v[56:59]
	v_mfma_f32_16x16x32_bf16 v[60:63], v[200:203], v[140:143], v[60:63]
	s_waitcnt vmcnt(8)
	ds_write_b128 v144, v[92:95] offset:61440
	s_waitcnt lgkmcnt(0)
	s_barrier
	ds_read_b128 v[128:131], v168 offset:32768
	ds_read_b128 v[132:135], v168 offset:34816
	ds_read_b128 v[136:139], v168 offset:36864
	ds_read_b128 v[140:143], v168 offset:38912
	ds_read_b128 v[188:191], v169 offset:32768
	ds_read_b128 v[192:195], v169 offset:34816
	ds_read_b128 v[196:199], v169 offset:36864
	ds_read_b128 v[200:203], v169 offset:38912
	v_mfma_f32_16x16x32_bf16 v[0:3], v[232:235], v[204:207], v[0:3]
	v_mfma_f32_16x16x32_bf16 v[4:7], v[236:239], v[204:207], v[4:7]
	v_lshl_add_u64 v[64:65], v[152:153], 0, s[18:19]
	global_load_dwordx4 v[64:67], v[64:65], off
	v_mfma_f32_16x16x32_bf16 v[8:11], v[240:243], v[204:207], v[8:11]
	v_mfma_f32_16x16x32_bf16 v[12:15], v[244:247], v[204:207], v[12:15]
	v_lshl_add_u64 v[68:69], v[154:155], 0, s[18:19]
	global_load_dwordx4 v[68:71], v[68:69], off
	v_mfma_f32_16x16x32_bf16 v[16:19], v[232:235], v[208:211], v[16:19]
	v_mfma_f32_16x16x32_bf16 v[20:23], v[236:239], v[208:211], v[20:23]
	v_lshl_add_u64 v[72:73], v[156:157], 0, s[18:19]
	global_load_dwordx4 v[72:75], v[72:73], off
	v_mfma_f32_16x16x32_bf16 v[24:27], v[240:243], v[208:211], v[24:27]
	v_mfma_f32_16x16x32_bf16 v[28:31], v[244:247], v[208:211], v[28:31]
	v_lshl_add_u64 v[76:77], v[158:159], 0, s[18:19]
	global_load_dwordx4 v[76:79], v[76:77], off
	v_mfma_f32_16x16x32_bf16 v[32:35], v[232:235], v[212:215], v[32:35]
	v_mfma_f32_16x16x32_bf16 v[36:39], v[236:239], v[212:215], v[36:39]
	v_lshl_add_u64 v[80:81], v[160:161], 0, s[18:19]
	global_load_dwordx4 v[80:83], v[80:81], off
	v_mfma_f32_16x16x32_bf16 v[40:43], v[240:243], v[212:215], v[40:43]
	v_mfma_f32_16x16x32_bf16 v[44:47], v[244:247], v[212:215], v[44:47]
	v_lshl_add_u64 v[84:85], v[162:163], 0, s[18:19]
	global_load_dwordx4 v[84:87], v[84:85], off
	v_mfma_f32_16x16x32_bf16 v[48:51], v[232:235], v[216:219], v[48:51]
	v_mfma_f32_16x16x32_bf16 v[52:55], v[236:239], v[216:219], v[52:55]
	v_lshl_add_u64 v[88:89], v[164:165], 0, s[18:19]
	global_load_dwordx4 v[88:91], v[88:89], off
	v_mfma_f32_16x16x32_bf16 v[56:59], v[240:243], v[216:219], v[56:59]
	v_mfma_f32_16x16x32_bf16 v[60:63], v[244:247], v[216:219], v[60:63]
	v_lshl_add_u64 v[92:93], v[166:167], 0, s[18:19]
	global_load_dwordx4 v[92:95], v[92:93], off
	s_waitcnt lgkmcnt(0)
	s_barrier
	ds_read_b128 v[204:207], v220 offset:32768
	ds_read_b128 v[208:211], v220 offset:34816
	ds_read_b128 v[212:215], v220 offset:36864
	ds_read_b128 v[216:219], v220 offset:38912
	ds_read_b128 v[232:235], v221 offset:32768
	ds_read_b128 v[236:239], v221 offset:34816
	ds_read_b128 v[240:243], v221 offset:36864
	ds_read_b128 v[244:247], v221 offset:38912
	s_min_u32 s5, s1, 39
	s_lshl_b32 s5, s5, 7
	s_add_i32 s18, s5, 0x200
	s_waitcnt lgkmcnt(8)
	v_mfma_f32_16x16x32_bf16 v[0:3], v[188:191], v[128:131], v[0:3]
	v_mfma_f32_16x16x32_bf16 v[4:7], v[192:195], v[128:131], v[4:7]
	s_waitcnt vmcnt(15)
	ds_write_b128 v144, v[96:99] offset:0
	v_mfma_f32_16x16x32_bf16 v[8:11], v[196:199], v[128:131], v[8:11]
	v_mfma_f32_16x16x32_bf16 v[12:15], v[200:203], v[128:131], v[12:15]
	s_waitcnt vmcnt(14)
	ds_write_b128 v144, v[100:103] offset:16384
	v_mfma_f32_16x16x32_bf16 v[16:19], v[188:191], v[132:135], v[16:19]
	v_mfma_f32_16x16x32_bf16 v[20:23], v[192:195], v[132:135], v[20:23]
	s_waitcnt vmcnt(13)
	ds_write_b128 v144, v[104:107] offset:4096
	v_mfma_f32_16x16x32_bf16 v[24:27], v[196:199], v[132:135], v[24:27]
	v_mfma_f32_16x16x32_bf16 v[28:31], v[200:203], v[132:135], v[28:31]
	s_waitcnt vmcnt(12)
	ds_write_b128 v144, v[108:111] offset:20480
	v_mfma_f32_16x16x32_bf16 v[32:35], v[188:191], v[136:139], v[32:35]
	v_mfma_f32_16x16x32_bf16 v[36:39], v[192:195], v[136:139], v[36:39]
	s_waitcnt vmcnt(11)
	ds_write_b128 v144, v[112:115] offset:8192
	v_mfma_f32_16x16x32_bf16 v[40:43], v[196:199], v[136:139], v[40:43]
	v_mfma_f32_16x16x32_bf16 v[44:47], v[200:203], v[136:139], v[44:47]
	s_waitcnt vmcnt(10)
	ds_write_b128 v144, v[116:119] offset:24576
	v_mfma_f32_16x16x32_bf16 v[48:51], v[188:191], v[140:143], v[48:51]
	v_mfma_f32_16x16x32_bf16 v[52:55], v[192:195], v[140:143], v[52:55]
	s_waitcnt vmcnt(9)
	ds_write_b128 v144, v[120:123] offset:12288
	v_mfma_f32_16x16x32_bf16 v[56:59], v[196:199], v[140:143], v[56:59]
	v_mfma_f32_16x16x32_bf16 v[60:63], v[200:203], v[140:143], v[60:63]
	s_waitcnt vmcnt(8)
	ds_write_b128 v144, v[124:127] offset:28672
	s_waitcnt lgkmcnt(0)
	s_barrier
; #define SB_ __builtin_amdgcn_sched_barrier(0)
; template <bool SWAP, bool HALF>
; DI void gemm_mainloop(const GemmDesc& d, int m0, int n0, bf16_t* smem, f32x16 (&acc)[2][2], int dry) {
;     ...
;   auto stage = [&](int cur, u32x4 (&ran)[4], u32x4 (&rbn)[4], int ks) {
;     ldf(cur, 1, 1); SB_;
;     mma(0); SB_;
;     ldf(cur, 2, 0); SB_;
;     lw(ran, rbn, cur ^ 1);
;     gl(ran, rbn, (ks + 3 < nk) ? ks + 3 : nk - 1);
;     SB_;
;     mma(1); SB_;
;     __syncthreads();
;     ldf(cur, 3, 1); SB_;
;     mma(0); SB_;
;     ldf(cur ^ 1, 0, 0);
;     SB_;
;     mma(1); SB_;
;     __syncthreads();
;   };
;   gl(ra0, rb0, 0);
;   gl(ra1, rb1, 1);
;   lw(ra0, rb0, 0);
;   gl(ra0, rb0, 2);
;   __syncthreads();
;   ldf(0, 0, 0);
; #pragma unroll 1
;   for (int ks = 0; ks < nk; ks += 2) {
;     stage(0, ra1, rb1, ks);
;     stage(1, ra0, rb0, ks + 1);
;   }
	ds_read_b128 v[128:131], v168 offset:0
	ds_read_b128 v[132:135], v168 offset:2048
	ds_read_b128 v[136:139], v168 offset:4096
	ds_read_b128 v[140:143], v168 offset:6144
	ds_read_b128 v[188:191], v169 offset:0
	ds_read_b128 v[192:195], v169 offset:2048
	ds_read_b128 v[196:199], v169 offset:4096
	ds_read_b128 v[200:203], v169 offset:6144
	v_mfma_f32_16x16x32_bf16 v[0:3], v[232:235], v[204:207], v[0:3]
	v_mfma_f32_16x16x32_bf16 v[4:7], v[236:239], v[204:207], v[4:7]
	v_lshl_add_u64 v[96:97], v[152:153], 0, s[18:19]
	global_load_dwordx4 v[96:99], v[96:97], off
	v_mfma_f32_16x16x32_bf16 v[8:11], v[240:243], v[204:207], v[8:11]
	v_mfma_f32_16x16x32_bf16 v[12:15], v[244:247], v[204:207], v[12:15]
	v_lshl_add_u64 v[100:101], v[154:155], 0, s[18:19]
	global_load_dwordx4 v[100:103], v[100:101], off
	v_mfma_f32_16x16x32_bf16 v[16:19], v[232:235], v[208:211], v[16:19]
	v_mfma_f32_16x16x32_bf16 v[20:23], v[236:239], v[208:211], v[20:23]
	v_lshl_add_u64 v[104:105], v[156:157], 0, s[18:19]
	global_load_dwordx4 v[104:107], v[104:105], off
	v_mfma_f32_16x16x32_bf16 v[24:27], v[240:243], v[208:211], v[24:27]
	v_mfma_f32_16x16x32_bf16 v[28:31], v[244:247], v[208:211], v[28:31]
	v_lshl_add_u64 v[108:109], v[158:159], 0, s[18:19]
	global_load_dwordx4 v[108:111], v[108:109], off
	v_mfma_f32_16x16x32_bf16 v[32:35], v[232:235], v[212:215], v[32:35]
	v_mfma_f32_16x16x32_bf16 v[36:39], v[236:239], v[212:215], v[36:39]
	v_lshl_add_u64 v[112:113], v[160:161], 0, s[18:19]
	global_load_dwordx4 v[112:115], v[112:113], off
	v_mfma_f32_16x16x32_bf16 v[40:43], v[240:243], v[212:215], v[40:43]
	v_mfma_f32_16x16x32_bf16 v[44:47], v[244:247], v[212:215], v[44:47]
	v_lshl_add_u64 v[116:117], v[162:163], 0, s[18:19]
	global_load_dwordx4 v[116:119], v[116:117], off
	v_mfma_f32_16x16x32_bf16 v[48:51], v[232:235], v[216:219], v[48:51]
	v_mfma_f32_16x16x32_bf16 v[52:55], v[236:239], v[216:219], v[52:55]
	v_lshl_add_u64 v[120:121], v[164:165], 0, s[18:19]
	global_load_dwordx4 v[120:123], v[120:121], off
	v_mfma_f32_16x16x32_bf16 v[56:59], v[240:243], v[216:219], v[56:59]
	v_mfma_f32_16x16x32_bf16 v[60:63], v[244:247], v[216:219], v[60:63]
	v_lshl_add_u64 v[124:125], v[166:167], 0, s[18:19]
	global_load_dwordx4 v[124:127], v[124:125], off
	s_add_i32 s5, s1, 2
	s_cmp_lt_u32 s1, 42
	s_mov_b32 s1, s5
	s_waitcnt lgkmcnt(0)
	s_barrier
	s_cbranch_scc1 .LBB0_1528
; DI float ssq_f(u64 v) { return (float)v * (1.f / 1048576.f); }
; DI void gemm_tile(const GemmDesc& d, int m0, int n0, bf16_t* smem, int dry) {
;     ...
;   if (d.epi == EPI_RESID) {
; #pragma unroll
;     for (int pass = 0; pass < 16; ++pass) {
;       int m = m0 + pass * 8 + (t >> 5); m = m < M ? m : M - 1;
;       hpre[pass] = *(const u32x2*)(d.hb + (size_t)m * D + d.c_off + n0 + (t & 31) * 4);
;     }
;   } else if (t < 128) {
;     rs_s[t] = rsqrtf(ssq_f(myss) * d.inv_dim + EPS);
;   }
;   if (half) {
; #pragma unroll
;     for (int a = 0; a < 2; ++a)
; #pragma unroll
;       for (int g = 0; g < 4; ++g) {
;         f32x4 o;
; #pragma unroll
;         for (int j = 0; j < 4; ++j) o[j] = acc[a][0][4 * g + j];
;         *(f32x4*)(Ct + (a * 32 + r) * CS + w * 32 + 8 * g + 4 * hh) = o;
;       }
;   } else {
; #pragma unroll
;     for (int a = 0; a < 2; ++a)
; #pragma unroll
;       for (int b = 0; b < 2; ++b)
; #pragma unroll
;         for (int g = 0; g < 4; ++g) {
;           f32x4 o;
; #pragma unroll
;           for (int j = 0; j < 4; ++j) o[j] = acc[a][b][4 * g + j];
;           *(f32x4*)(Ct + (wm * 64 + a * 32 + r) * CS + wn * 64 + b * 32 + 8 * g + 4 * hh) = o;
;         }
;   }
;   __syncthreads();
;   if (d.epi == EPI_RESID) {
; #pragma unroll
;     for (int pass = 0; pass < 16; ++pass) {
;       const int row = pass * 8 + (t >> 5), c4 = t & 31, m = m0 + row;
;       float part = 0.f;
;       if (m < M) {
;         const f32x4 v = *(const f32x4*)(Ct + row * CS + c4 * 4);
;         const int n = d.c_off + n0 + c4 * 4;
;         f32x4 hv;
;         hv[0] = __uint_as_float(hpre[pass][0] << 16); hv[1] = __uint_as_float(hpre[pass][0] & 0xffff0000u);
;         hv[2] = __uint_as_float(hpre[pass][1] << 16); hv[3] = __uint_as_float(hpre[pass][1] & 0xffff0000u);
; #pragma unroll
;         for (int j = 0; j < 4; ++j) { hv[j] += v[j]; part += hv[j] * hv[j]; }
;         u32x2 o; o[0] = pk_bf16(hv[0], hv[1]); o[1] = pk_bf16(hv[2], hv[3]);
;         *(u32x2*)(d.hb + (size_t)m * D + n) = o;
;       }
	s_waitcnt vmcnt(7)
	v_ashrrev_i32_e32 v98, 5, v150
	v_add_u32_e32 v92, s13, v98
	s_ashr_i32 s5, s4, 31
	s_lshl_b64 s[10:11], s[4:5], 1
	v_add_u32_e32 v70, 16, v92
	v_add_u32_e32 v72, 24, v92
	s_add_u32 s10, s56, s10
	v_lshlrev_b32_e32 v64, 3, v150
	v_min_i32_e32 v66, 0x803f, v92
	v_add_u32_e32 v68, 8, v92
	v_min_i32_e32 v70, 0x803f, v70
	v_min_i32_e32 v72, 0x803f, v72
	s_addc_u32 s11, s57, s11
	v_and_b32_e32 v144, 0xf8, v64
	v_ashrrev_i32_e32 v67, 31, v66
	v_min_i32_e32 v68, 0x803f, v68
	v_ashrrev_i32_e32 v71, 31, v70
	v_ashrrev_i32_e32 v73, 31, v72
	v_lshl_add_u64 v[64:65], s[10:11], 0, v[144:145]
	v_lshlrev_b64 v[66:67], 11, v[66:67]
	v_ashrrev_i32_e32 v69, 31, v68
	v_lshlrev_b64 v[70:71], 11, v[70:71]
	v_lshlrev_b64 v[72:73], 11, v[72:73]
	v_lshl_add_u64 v[66:67], v[64:65], 0, v[66:67]
	v_lshlrev_b64 v[68:69], 11, v[68:69]
	v_lshl_add_u64 v[70:71], v[64:65], 0, v[70:71]
	v_lshl_add_u64 v[72:73], v[64:65], 0, v[72:73]
	v_lshl_add_u64 v[68:69], v[64:65], 0, v[68:69]
	global_load_dwordx2 v[96:97], v[66:67], off
	global_load_dwordx2 v[94:95], v[68:69], off
	global_load_dwordx2 v[90:91], v[70:71], off
	global_load_dwordx2 v[88:89], v[72:73], off
	v_add_u32_e32 v66, 32, v92
	v_add_u32_e32 v70, 48, v92
	v_add_u32_e32 v72, 56, v92
	v_min_i32_e32 v66, 0x803f, v66
	v_add_u32_e32 v68, 40, v92
	v_min_i32_e32 v70, 0x803f, v70
	v_min_i32_e32 v72, 0x803f, v72
	v_ashrrev_i32_e32 v67, 31, v66
	v_min_i32_e32 v68, 0x803f, v68
	v_ashrrev_i32_e32 v71, 31, v70
	v_ashrrev_i32_e32 v73, 31, v72
	v_lshlrev_b64 v[66:67], 11, v[66:67]
	v_ashrrev_i32_e32 v69, 31, v68
	v_lshlrev_b64 v[70:71], 11, v[70:71]
	v_lshlrev_b64 v[72:73], 11, v[72:73]
	v_lshl_add_u64 v[66:67], v[64:65], 0, v[66:67]
	v_lshlrev_b64 v[68:69], 11, v[68:69]
	v_lshl_add_u64 v[70:71], v[64:65], 0, v[70:71]
	v_lshl_add_u64 v[72:73], v[64:65], 0, v[72:73]
	v_lshl_add_u64 v[68:69], v[64:65], 0, v[68:69]
	global_load_dwordx2 v[86:87], v[66:67], off
	global_load_dwordx2 v[84:85], v[68:69], off
	global_load_dwordx2 v[82:83], v[70:71], off
	global_load_dwordx2 v[80:81], v[72:73], off
	v_add_u32_e32 v66, 64, v92
	v_add_u32_e32 v70, 0x50, v92
	v_add_u32_e32 v72, 0x58, v92
	v_min_i32_e32 v66, 0x803f, v66
	v_add_u32_e32 v68, 0x48, v92
	v_min_i32_e32 v70, 0x803f, v70
	v_min_i32_e32 v72, 0x803f, v72
	v_ashrrev_i32_e32 v67, 31, v66
	v_min_i32_e32 v68, 0x803f, v68
	v_ashrrev_i32_e32 v71, 31, v70
	v_ashrrev_i32_e32 v73, 31, v72
	v_lshlrev_b64 v[66:67], 11, v[66:67]
	v_ashrrev_i32_e32 v69, 31, v68
	v_lshlrev_b64 v[70:71], 11, v[70:71]
	v_lshlrev_b64 v[72:73], 11, v[72:73]
	v_lshl_add_u64 v[66:67], v[64:65], 0, v[66:67]
	v_lshlrev_b64 v[68:69], 11, v[68:69]
	v_lshl_add_u64 v[70:71], v[64:65], 0, v[70:71]
	v_lshl_add_u64 v[72:73], v[64:65], 0, v[72:73]
	v_lshl_add_u64 v[68:69], v[64:65], 0, v[68:69]
	global_load_dwordx2 v[78:79], v[66:67], off
	global_load_dwordx2 v[76:77], v[68:69], off
	global_load_dwordx2 v[74:75], v[70:71], off
	s_nop 0
	global_load_dwordx2 v[72:73], v[72:73], off
	v_add_u32_e32 v70, 0x70, v92
	v_min_i32_e32 v70, 0x803f, v70
	v_ashrrev_i32_e32 v71, 31, v70
	v_lshlrev_b64 v[70:71], 11, v[70:71]
	v_add_u32_e32 v66, 0x60, v92
	v_add_u32_e32 v68, 0x68, v92
	s_waitcnt vmcnt(18)
	v_lshl_add_u64 v[100:101], v[64:65], 0, v[70:71]
	v_add_u32_e32 v70, 0x78, v92
	v_min_i32_e32 v66, 0x803f, v66
	v_min_i32_e32 v68, 0x803f, v68
	v_min_i32_e32 v70, 0x803f, v70
	v_ashrrev_i32_e32 v67, 31, v66
	v_ashrrev_i32_e32 v69, 31, v68
	v_ashrrev_i32_e32 v71, 31, v70
	v_lshlrev_b64 v[66:67], 11, v[66:67]
	v_lshlrev_b64 v[68:69], 11, v[68:69]
	v_lshlrev_b64 v[70:71], 11, v[70:71]
	v_lshl_add_u64 v[66:67], v[64:65], 0, v[66:67]
	v_lshl_add_u64 v[68:69], v[64:65], 0, v[68:69]
	v_lshl_add_u64 v[64:65], v[64:65], 0, v[70:71]
	global_load_dwordx2 v[70:71], v[66:67], off
	s_nop 0
	global_load_dwordx2 v[68:69], v[68:69], off
	s_nop 0
	global_load_dwordx2 v[66:67], v[100:101], off
	s_nop 0
	global_load_dwordx2 v[64:65], v[64:65], off
	v_and_b32_e32 v99, 31, v150
	v_lshrrev_b32_e32 v100, 1, v150
	v_lshlrev_b32_e32 v93, 2, v150
	v_and_or_b32 v101, v100, s72, v99
	v_and_b32_e32 v100, 16, v100
	s_movk_i32 s1, 0x100
	v_and_or_b32 v100, v93, s1, v100
	v_mad_u64_u32 v[100:101], s[10:11], v101, s22, v[100:101]
	v_and_b32_e32 v204, 15, v150
	v_lshrrev_b32_e32 v205, 1, v150
	v_and_or_b32 v204, v205, s72, v204
	v_lshlrev_b32_e32 v205, 2, v150
	v_and_b32_e32 v206, 0x30, v150
	v_and_b32_e32 v205, 0x100, v205
	v_or_b32_e32 v205, v205, v206
	v_mad_u32_u24 v100, v204, s22, v205
	ds_write_b128 v100, v[0:3]
	ds_write_b128 v100, v[4:7] offset:64
	ds_write_b128 v100, v[8:11] offset:128
	ds_write_b128 v100, v[12:15] offset:192
	ds_write_b128 v100, v[16:19] offset:8448
	ds_write_b128 v100, v[20:23] offset:8512
	ds_write_b128 v100, v[24:27] offset:8576
	ds_write_b128 v100, v[28:31] offset:8640
	ds_write_b128 v100, v[32:35] offset:16896
	ds_write_b128 v100, v[36:39] offset:16960
	ds_write_b128 v100, v[40:43] offset:17024
	ds_write_b128 v100, v[44:47] offset:17088
	ds_write_b128 v100, v[48:51] offset:25344
	ds_write_b128 v100, v[52:55] offset:25408
	ds_write_b128 v100, v[56:59] offset:25472
	ds_write_b128 v100, v[60:63] offset:25536
	v_lshl_or_b32 v0, v99, 2, s4
	v_lshlrev_b32_e32 v2, 4, v99
	v_cmp_gt_i32_e64 s[4:5], s23, v92
	v_mov_b32_e32 v4, 0
	v_ashrrev_i32_e32 v93, 31, v92
	v_ashrrev_i32_e32 v1, 31, v0
	s_waitcnt lgkmcnt(0)
	s_barrier
	s_and_saveexec_b64 s[10:11], s[4:5]
	s_cbranch_execz .LBB0_1531
	v_mad_u64_u32 v[4:5], s[14:15], v98, s22, v[2:3]
	ds_read_b128 v[4:7], v4
	s_waitcnt vmcnt(15)
	v_lshlrev_b32_e32 v8, 16, v96
	v_and_b32_e32 v9, 0xffff0000, v96
	v_and_b32_e32 v11, 0xffff0000, v97
	v_lshlrev_b32_e32 v10, 16, v97
	s_waitcnt lgkmcnt(0)
	v_pk_add_f32 v[8:9], v[4:5], v[8:9]
	v_pk_add_f32 v[6:7], v[6:7], v[10:11]
	v_pk_mul_f32 v[4:5], v[8:9], v[8:9]
	v_pk_mul_f32 v[10:11], v[6:7], v[6:7]
	v_add_f32_e32 v3, v4, v5
	v_cvt_pk_bf16_f32 v8, v8, v9
	v_cvt_pk_bf16_f32 v9, v6, v7
	v_lshlrev_b64 v[6:7], 11, v[92:93]
	v_add_f32_e32 v3, v10, v3
	v_lshl_add_u64 v[6:7], s[56:57], 0, v[6:7]
	v_add_f32_e32 v4, v11, v3
	v_lshl_add_u64 v[6:7], v[0:1], 1, v[6:7]
	global_store_dwordx2 v[6:7], v[8:9], off

; __global__ void __launch_bounds__(NTHREADS, 2) fwd_kernel(Params p, int ph_begin, int ph_end) {
;   __shared__ __attribute__((aligned(16))) unsigned char smem_raw[SMEM_BYTES];
	.amdhsa_kernel _Z10fwd_kernel6Paramsii
		.amdhsa_group_segment_fixed_size 73744
		.amdhsa_private_segment_fixed_size 0
		.amdhsa_kernarg_size 2824
		.amdhsa_user_sgpr_count 2
		.amdhsa_user_sgpr_dispatch_ptr 0
		.amdhsa_user_sgpr_queue_ptr 0
		.amdhsa_user_sgpr_kernarg_segment_ptr 1
		.amdhsa_user_sgpr_dispatch_id 0
		.amdhsa_user_sgpr_kernarg_preload_length 0
		.amdhsa_user_sgpr_kernarg_preload_offset 0
		.amdhsa_user_sgpr_private_segment_size 0
		.amdhsa_uses_dynamic_stack 0
		.amdhsa_enable_private_segment 0
		.amdhsa_system_sgpr_workgroup_id_x 1
		.amdhsa_system_sgpr_workgroup_id_y 0
		.amdhsa_system_sgpr_workgroup_id_z 0
		.amdhsa_system_sgpr_workgroup_info 0
		.amdhsa_system_vgpr_workitem_id 2
		.amdhsa_next_free_vgpr 248
		.amdhsa_next_free_sgpr 100
		.amdhsa_accum_offset 248
		.amdhsa_reserve_vcc 1
		.amdhsa_float_round_mode_32 0
		.amdhsa_float_round_mode_16_64 0
		.amdhsa_float_denorm_mode_32 3
		.amdhsa_float_denorm_mode_16_64 3
		.amdhsa_dx10_clamp 1
		.amdhsa_ieee_mode 1
		.amdhsa_fp16_overflow 0
		.amdhsa_tg_split 0
		.amdhsa_exception_fp_ieee_invalid_op 0
		.amdhsa_exception_fp_denorm_src 0
		.amdhsa_exception_fp_ieee_div_zero 0
		.amdhsa_exception_fp_ieee_overflow 0
		.amdhsa_exception_fp_ieee_underflow 0
		.amdhsa_exception_fp_ieee_inexact 0
		.amdhsa_exception_int_div_zero 0
	.end_amdhsa_kernel

; __global__ void __launch_bounds__(NTHREADS, 2) fwd_kernel(Params p, int ph_begin, int ph_end) {
;   __shared__ __attribute__((aligned(16))) unsigned char smem_raw[SMEM_BYTES];
amdhsa.kernels:
  - .agpr_count:     0
    .args:
      - .offset:         0
        .size:           2560
        .value_kind:     by_value
      - .offset:         2560
        .size:           4
        .value_kind:     by_value
      - .offset:         2564
        .size:           4
        .value_kind:     by_value
      - .offset:         2568
        .size:           4
        .value_kind:     hidden_block_count_x
      - .offset:         2572
        .size:           4
        .value_kind:     hidden_block_count_y
      - .offset:         2576
        .size:           4
        .value_kind:     hidden_block_count_z
      - .offset:         2580
        .size:           2
        .value_kind:     hidden_group_size_x
      - .offset:         2582
        .size:           2
        .value_kind:     hidden_group_size_y
      - .offset:         2584
        .size:           2
        .value_kind:     hidden_group_size_z
      - .offset:         2586
        .size:           2
        .value_kind:     hidden_remainder_x
      - .offset:         2588
        .size:           2
        .value_kind:     hidden_remainder_y
      - .offset:         2590
        .size:           2
        .value_kind:     hidden_remainder_z
      - .offset:         2608
        .size:           8
        .value_kind:     hidden_global_offset_x
      - .offset:         2616
        .size:           8
        .value_kind:     hidden_global_offset_y
      - .offset:         2624
        .size:           8
        .value_kind:     hidden_global_offset_z
      - .offset:         2632
        .size:           2
        .value_kind:     hidden_grid_dims
      - .offset:         2656
        .size:           8
        .value_kind:     hidden_multigrid_sync_arg
    .group_segment_fixed_size: 73744
    .kernarg_segment_align: 8
    .kernarg_segment_size: 2824
    .language:       OpenCL C
    .language_version:
      - 2
      - 0
    .max_flat_workgroup_size: 256
    .name:           _Z10fwd_kernel6Paramsii
    .private_segment_fixed_size: 0
    .sgpr_count:     106
    .sgpr_spill_count: 163
    .symbol:         _Z10fwd_kernel6Paramsii.kd
    .uniform_work_group_size: 1
    .uses_dynamic_stack: false
    .vgpr_count:     248
    .vgpr_spill_count: 0
    .wavefront_size: 64
